# only the f32 residual-stream stores of the residual-GEMM epilogue made write-through (sc1); bf16 copies stay cached
# speedup vs baseline: 1.0030x; 1.0030x over previous
; __device__ __forceinline__ unsigned pk2(float lo, float hi) { return pg8::cvt_pk_bf16(lo, hi); }
;     __device__ __forceinline__ void operator()(const pg8::f32x4 (&acc)[2][2][4][2], const pg8::Unit& u, int wr, int wc, int fr, int fq) const {
;         const int row0 = u.pm * 256 + wr * 64 + fr, col0 = u.pn * 256 + wc * 32 + 8 * fq;
; #pragma unroll
;         for (int ai = 0; ai < 2; ++ai) {
;             f32x4 bv[4][2][2];
; #pragma unroll
;             for (int m = 0; m < 4; ++m)
; #pragma unroll
;                 for (int bj = 0; bj < 2; ++bj) { const size_t off = (size_t)(row0 + ai * 128 + m * 16) * DM + col0 + bj * 128; bv[m][bj][0] = *(const f32x4*)(base + off); bv[m][bj][1] = *(const f32x4*)(base + off + 4); }
; #pragma unroll
;             for (int m = 0; m < 4; ++m) {
;                 const int row = row0 + ai * 128 + m * 16; float ss = 0.f;
; #pragma unroll
;                 for (int bj = 0; bj < 2; ++bj) {
;                     const size_t off = (size_t)row * DM + col0 + bj * 128;
;                     const f32x4 x0 = bv[m][bj][0] + acc[ai][bj][m][0] * alpha, x1 = bv[m][bj][1] + acc[ai][bj][m][1] * alpha;
;                     *(f32x4*)(out + off) = x0; *(f32x4*)(out + off + 4) = x1;
;                     u32x4 w; w.x = pk2(x0[0], x0[1]); w.y = pk2(x0[2], x0[3]); w.z = pk2(x1[0], x1[1]); w.w = pk2(x1[2], x1[3]);
;                     *(u32x4*)(xb + off) = w;
;                     ss += ((x0[0] * x0[0] + x0[1] * x0[1]) + (x0[2] * x0[2] + x0[3] * x0[3])) + ((x1[0] * x1[0] + x1[1] * x1[1]) + (x1[2] * x1[2] + x1[3] * x1[3]));
;                 }
;                 ss += __shfl_xor(ss, 16); ss += __shfl_xor(ss, 32);
;                 if (ssq && fq == 0) ssq[(size_t)row * 16 + u.pn * 4 + wc] = ss;
;             }
.LBB0_592:
	v_xor_b32_e32 v132, 16, v233
	v_cmp_lt_i32_e32 vcc, v132, v234
	v_lshl_add_u32 v208, s59, 8, v35
	v_lshl_or_b32 v206, s8, 8, v219
	v_cndmask_b32_e32 v132, v233, v132, vcc
	v_lshlrev_b32_e32 v222, 2, v132
	v_xor_b32_e32 v132, 32, v233
	v_cmp_lt_i32_e32 vcc, v132, v234
	v_ashrrev_i32_e32 v207, 31, v206
	v_ashrrev_i32_e32 v209, 31, v208
	v_cndmask_b32_e32 v132, v233, v132, vcc
	v_lshlrev_b32_e32 v221, 2, v132
	v_lshl_add_u64 v[210:211], v[206:207], 2, s[12:13]
	v_lshlrev_b64 v[132:133], 12, v[208:209]
	v_lshl_add_u64 v[132:133], v[210:211], 0, v[132:133]
	global_load_dwordx4 v[224:227], v[132:133], off offset:16
	global_load_dwordx4 v[248:251], v[132:133], off
	global_load_dwordx4 v[180:183], v[132:133], off offset:528
	global_load_dwordx4 v[184:187], v[132:133], off offset:512
	v_or_b32_e32 v216, 16, v208
	v_ashrrev_i32_e32 v217, 31, v216
	v_lshlrev_b64 v[132:133], 12, v[216:217]
	v_or_b32_e32 v214, 32, v208
	v_lshl_add_u64 v[132:133], v[210:211], 0, v[132:133]
	v_ashrrev_i32_e32 v215, 31, v214
	global_load_dwordx4 v[172:175], v[132:133], off offset:16
	global_load_dwordx4 v[176:179], v[132:133], off
	global_load_dwordx4 v[164:167], v[132:133], off offset:528
	global_load_dwordx4 v[168:171], v[132:133], off offset:512
	v_lshlrev_b64 v[132:133], 12, v[214:215]
	v_or_b32_e32 v212, 48, v208
	v_lshl_add_u64 v[132:133], v[210:211], 0, v[132:133]
	v_ashrrev_i32_e32 v213, 31, v212
	global_load_dwordx4 v[156:159], v[132:133], off offset:16
	global_load_dwordx4 v[160:163], v[132:133], off
	global_load_dwordx4 v[140:143], v[132:133], off offset:528
	global_load_dwordx4 v[148:151], v[132:133], off offset:512
	v_lshlrev_b64 v[132:133], 12, v[212:213]
	v_lshl_add_u64 v[136:137], v[210:211], 0, v[132:133]
	global_load_dwordx4 v[144:147], v[136:137], off offset:16
	global_load_dwordx4 v[152:155], v[136:137], off
	global_load_dwordx4 v[132:135], v[136:137], off offset:528
	s_nop 0
	global_load_dwordx4 v[136:139], v[136:137], off offset:512
	v_lshlrev_b64 v[236:237], 10, v[208:209]
	v_lshl_add_u64 v[236:237], v[236:237], 0, v[206:207]
	v_mov_b32_e32 v193, v192
	v_lshl_add_u64 v[238:239], v[236:237], 2, s[24:25]
	v_lshlrev_b64 v[236:237], 1, v[236:237]
	v_lshl_add_u64 v[240:241], s[2:3], 0, v[236:237]
	s_lshl_b32 s22, s8, 2
	v_or_b32_e32 v236, 0x100, v236
	s_ashr_i32 s23, s22, 31
	s_waitcnt vmcnt(0)
	v_pk_fma_f32 v[124:125], v[194:195], v[124:125], v[224:225]
	v_pk_fma_f32 v[130:131], v[192:193], v[130:131], v[250:251]
	v_pk_fma_f32 v[128:129], v[194:195], v[128:129], v[248:249]
	v_pk_fma_f32 v[126:127], v[192:193], v[126:127], v[226:227]
	global_store_dwordx4 v[238:239], v[128:131], off sc1
	global_store_dwordx4 v[238:239], v[124:127], off offset:16 sc1
	v_cvt_pk_bf16_f32 v224, v128, v129
	v_cvt_pk_bf16_f32 v226, v124, v125
	v_mul_f32_e32 v129, v129, v129
	v_mul_f32_e32 v125, v125, v125
	v_fmac_f32_e32 v129, v128, v128
	v_mul_f32_e32 v128, v131, v131
	v_fmac_f32_e32 v125, v124, v124
	v_mul_f32_e32 v124, v127, v127
	v_fmac_f32_e32 v128, v130, v130
	v_fmac_f32_e32 v124, v126, v126
	v_cvt_pk_bf16_f32 v225, v130, v131
	v_cvt_pk_bf16_f32 v227, v126, v127
	v_add_f32_e32 v128, v129, v128
	v_add_f32_e32 v124, v125, v124
	v_pk_fma_f32 v[122:123], v[192:193], v[122:123], v[186:187]
	v_pk_fma_f32 v[120:121], v[194:195], v[120:121], v[184:185]
	v_pk_fma_f32 v[116:117], v[194:195], v[116:117], v[180:181]
	global_store_dwordx4 v[240:241], v[224:227], off
	v_add_f32_e32 v130, v128, v124
	v_pk_fma_f32 v[118:119], v[192:193], v[118:119], v[182:183]
	global_store_dwordx4 v[238:239], v[120:123], off offset:512 sc1
	global_store_dwordx4 v[238:239], v[116:119], off offset:528 sc1
	v_cvt_pk_bf16_f32 v124, v120, v121
	v_cvt_pk_bf16_f32 v126, v116, v117
	v_mul_f32_e32 v121, v121, v121
	v_mul_f32_e32 v117, v117, v117
	v_fmac_f32_e32 v121, v120, v120
	v_mul_f32_e32 v120, v123, v123
	v_fmac_f32_e32 v117, v116, v116
	v_mul_f32_e32 v116, v119, v119
	v_fmac_f32_e32 v120, v122, v122
	v_fmac_f32_e32 v116, v118, v118
	v_add_f32_e32 v120, v121, v120
	v_add_f32_e32 v116, v117, v116
	v_add_f32_e32 v116, v120, v116
	v_add_f32_e32 v116, v130, v116
	ds_bpermute_b32 v117, v222, v116
	v_cvt_pk_bf16_f32 v125, v122, v123
	v_cvt_pk_bf16_f32 v127, v118, v119
	v_lshl_add_u64 v[128:129], s[2:3], 0, v[236:237]
	global_store_dwordx4 v[128:129], v[124:127], off
	s_waitcnt lgkmcnt(0)
	v_add_f32_e32 v116, v116, v117
	ds_bpermute_b32 v117, v221, v116
	s_and_saveexec_b64 s[40:41], s[18:19]
	s_cbranch_execz .LBB0_594
	s_waitcnt lgkmcnt(0)
	v_add_f32_e32 v118, v116, v117
	v_lshlrev_b64 v[116:117], 6, v[208:209]
	v_lshl_add_u64 v[116:117], s[14:15], 0, v[116:117]
	v_lshl_add_u64 v[116:117], s[22:23], 2, v[116:117]
	s_lshl_b32 s8, s54, 2
	v_lshl_add_u64 v[116:117], v[116:117], 0, s[8:9]
	global_store_dword v[116:117], v118, off
; __device__ __forceinline__ unsigned pk2(float lo, float hi) { return pg8::cvt_pk_bf16(lo, hi); }
;     __device__ __forceinline__ void operator()(const pg8::f32x4 (&acc)[2][2][4][2], const pg8::Unit& u, int wr, int wc, int fr, int fq) const {
;     ...
;             for (int m = 0; m < 4; ++m) {
;                 const int row = row0 + ai * 128 + m * 16; float ss = 0.f;
; #pragma unroll
;                 for (int bj = 0; bj < 2; ++bj) {
;                     const size_t off = (size_t)row * DM + col0 + bj * 128;
;                     const f32x4 x0 = bv[m][bj][0] + acc[ai][bj][m][0] * alpha, x1 = bv[m][bj][1] + acc[ai][bj][m][1] * alpha;
;                     *(f32x4*)(out + off) = x0; *(f32x4*)(out + off + 4) = x1;
;                     u32x4 w; w.x = pk2(x0[0], x0[1]); w.y = pk2(x0[2], x0[3]); w.z = pk2(x1[0], x1[1]); w.w = pk2(x1[2], x1[3]);
;                     *(u32x4*)(xb + off) = w;
;                     ss += ((x0[0] * x0[0] + x0[1] * x0[1]) + (x0[2] * x0[2] + x0[3] * x0[3])) + ((x1[0] * x1[0] + x1[1] * x1[1]) + (x1[2] * x1[2] + x1[3] * x1[3]));
;                 }
;                 ss += __shfl_xor(ss, 16); ss += __shfl_xor(ss, 32);
;                 if (ssq && fq == 0) ssq[(size_t)row * 16 + u.pn * 4 + wc] = ss;
;             }
.LBB0_594:
	s_or_b64 exec, exec, s[40:41]
	s_waitcnt lgkmcnt(0)
	v_lshlrev_b64 v[116:117], 10, v[216:217]
	v_lshl_add_u64 v[120:121], v[116:117], 0, v[206:207]
	v_pk_fma_f32 v[114:115], v[192:193], v[114:115], v[178:179]
	v_pk_fma_f32 v[112:113], v[194:195], v[112:113], v[176:177]
	v_pk_fma_f32 v[108:109], v[194:195], v[108:109], v[172:173]
	v_lshl_add_u64 v[122:123], v[120:121], 2, s[24:25]
	v_pk_fma_f32 v[110:111], v[192:193], v[110:111], v[174:175]
	global_store_dwordx4 v[122:123], v[112:115], off sc1
	global_store_dwordx4 v[122:123], v[108:111], off offset:16 sc1
	v_cvt_pk_bf16_f32 v118, v108, v109
	v_pk_fma_f32 v[106:107], v[192:193], v[106:107], v[170:171]
	v_mul_f32_e32 v109, v109, v109
	v_fmac_f32_e32 v109, v108, v108
	v_mul_f32_e32 v108, v111, v111
	v_fmac_f32_e32 v108, v110, v110
	v_pk_fma_f32 v[104:105], v[194:195], v[104:105], v[168:169]
	v_cvt_pk_bf16_f32 v119, v110, v111
	v_add_f32_e32 v108, v109, v108
	v_mul_f32_e32 v109, v105, v105
	v_mul_f32_e32 v110, v107, v107
	v_cvt_pk_bf16_f32 v116, v112, v113
	v_mul_f32_e32 v113, v113, v113
	v_pk_fma_f32 v[102:103], v[192:193], v[102:103], v[166:167]
	v_pk_fma_f32 v[100:101], v[194:195], v[100:101], v[164:165]
	v_fmac_f32_e32 v109, v104, v104
	v_fmac_f32_e32 v110, v106, v106
	v_fmac_f32_e32 v113, v112, v112
	v_mul_f32_e32 v112, v115, v115
	v_add_f32_e32 v109, v109, v110
	v_mul_f32_e32 v110, v101, v101
	v_mul_f32_e32 v111, v103, v103
	v_fmac_f32_e32 v112, v114, v114
	v_fmac_f32_e32 v110, v100, v100
	v_fmac_f32_e32 v111, v102, v102
	v_add_f32_e32 v112, v113, v112
	v_add_f32_e32 v110, v110, v111
	v_add_f32_e32 v108, v112, v108
	v_add_f32_e32 v109, v109, v110
	v_add_f32_e32 v108, v108, v109
	ds_bpermute_b32 v109, v222, v108
	v_lshlrev_b64 v[120:121], 1, v[120:121]
	v_cvt_pk_bf16_f32 v117, v114, v115
	v_lshl_add_u64 v[124:125], s[2:3], 0, v[120:121]
	global_store_dwordx4 v[124:125], v[116:119], off
	global_store_dwordx4 v[122:123], v[104:107], off offset:512 sc1
	global_store_dwordx4 v[122:123], v[100:103], off offset:528 sc1
	v_or_b32_e32 v120, 0x100, v120
	v_cvt_pk_bf16_f32 v104, v104, v105
	v_cvt_pk_bf16_f32 v105, v106, v107
	v_cvt_pk_bf16_f32 v106, v100, v101
	s_waitcnt lgkmcnt(0)
	v_add_f32_e32 v100, v108, v109
	ds_bpermute_b32 v101, v221, v100
	v_cvt_pk_bf16_f32 v107, v102, v103
	v_lshl_add_u64 v[102:103], s[2:3], 0, v[120:121]
	global_store_dwordx4 v[102:103], v[104:107], off
	s_and_saveexec_b64 s[40:41], s[18:19]
	s_cbranch_execz .LBB0_596
	s_waitcnt lgkmcnt(0)
	v_add_f32_e32 v102, v100, v101
	v_lshlrev_b64 v[100:101], 6, v[216:217]
	v_lshl_add_u64 v[100:101], s[14:15], 0, v[100:101]
	v_lshl_add_u64 v[100:101], s[22:23], 2, v[100:101]
	s_lshl_b32 s8, s54, 2
	v_lshl_add_u64 v[100:101], v[100:101], 0, s[8:9]
	global_store_dword v[100:101], v102, off
.LBB0_596:
	s_or_b64 exec, exec, s[40:41]
	s_waitcnt lgkmcnt(0)
	v_lshlrev_b64 v[100:101], 10, v[214:215]
	v_lshl_add_u64 v[104:105], v[100:101], 0, v[206:207]
	v_mov_b32_e32 v193, v192
	v_pk_fma_f32 v[98:99], v[192:193], v[98:99], v[162:163]
	v_pk_fma_f32 v[96:97], v[194:195], v[96:97], v[160:161]
	v_pk_fma_f32 v[92:93], v[194:195], v[92:93], v[156:157]
	v_lshl_add_u64 v[106:107], v[104:105], 2, s[24:25]
	v_pk_fma_f32 v[94:95], v[192:193], v[94:95], v[158:159]
	global_store_dwordx4 v[106:107], v[96:99], off sc1
	global_store_dwordx4 v[106:107], v[92:95], off offset:16 sc1
	v_cvt_pk_bf16_f32 v102, v92, v93
	v_pk_fma_f32 v[90:91], v[192:193], v[90:91], v[150:151]
	v_mul_f32_e32 v93, v93, v93
	v_fmac_f32_e32 v93, v92, v92
	v_mul_f32_e32 v92, v95, v95
	v_fmac_f32_e32 v92, v94, v94
	v_pk_fma_f32 v[88:89], v[194:195], v[88:89], v[148:149]
	v_cvt_pk_bf16_f32 v103, v94, v95
	v_add_f32_e32 v92, v93, v92
	v_mul_f32_e32 v93, v89, v89
	v_mul_f32_e32 v94, v91, v91
	v_cvt_pk_bf16_f32 v100, v96, v97
	v_mul_f32_e32 v97, v97, v97
	v_pk_fma_f32 v[86:87], v[192:193], v[86:87], v[142:143]
	v_pk_fma_f32 v[84:85], v[194:195], v[84:85], v[140:141]
	v_fmac_f32_e32 v93, v88, v88
	v_fmac_f32_e32 v94, v90, v90
	v_fmac_f32_e32 v97, v96, v96
	v_mul_f32_e32 v96, v99, v99
	v_add_f32_e32 v93, v93, v94
	v_mul_f32_e32 v94, v85, v85
	v_mul_f32_e32 v95, v87, v87
	v_fmac_f32_e32 v96, v98, v98
	v_fmac_f32_e32 v94, v84, v84
	v_fmac_f32_e32 v95, v86, v86
	v_add_f32_e32 v96, v97, v96
	v_add_f32_e32 v94, v94, v95
	v_add_f32_e32 v92, v96, v92
	v_add_f32_e32 v93, v93, v94
	v_add_f32_e32 v92, v92, v93
	ds_bpermute_b32 v93, v222, v92
	v_lshlrev_b64 v[104:105], 1, v[104:105]
	v_cvt_pk_bf16_f32 v101, v98, v99
	v_lshl_add_u64 v[108:109], s[2:3], 0, v[104:105]
	global_store_dwordx4 v[108:109], v[100:103], off
	global_store_dwordx4 v[106:107], v[88:91], off offset:512 sc1
	global_store_dwordx4 v[106:107], v[84:87], off offset:528 sc1
	v_or_b32_e32 v104, 0x100, v104
	v_cvt_pk_bf16_f32 v88, v88, v89
	v_cvt_pk_bf16_f32 v89, v90, v91
	v_cvt_pk_bf16_f32 v90, v84, v85
	s_waitcnt lgkmcnt(0)
	v_add_f32_e32 v84, v92, v93
	ds_bpermute_b32 v85, v221, v84
	v_cvt_pk_bf16_f32 v91, v86, v87
	v_lshl_add_u64 v[86:87], s[2:3], 0, v[104:105]
	global_store_dwordx4 v[86:87], v[88:91], off
	s_and_saveexec_b64 s[40:41], s[18:19]
	s_cbranch_execz .LBB0_598
	s_waitcnt lgkmcnt(0)
	v_add_f32_e32 v86, v84, v85
	v_lshlrev_b64 v[84:85], 6, v[214:215]
	v_lshl_add_u64 v[84:85], s[14:15], 0, v[84:85]
	v_lshl_add_u64 v[84:85], s[22:23], 2, v[84:85]
	s_lshl_b32 s8, s54, 2
	v_lshl_add_u64 v[84:85], v[84:85], 0, s[8:9]
	global_store_dword v[84:85], v86, off
; __device__ __forceinline__ unsigned pk2(float lo, float hi) { return pg8::cvt_pk_bf16(lo, hi); }
;     __device__ __forceinline__ void operator()(const pg8::f32x4 (&acc)[2][2][4][2], const pg8::Unit& u, int wr, int wc, int fr, int fq) const {
;     ...
;         for (int ai = 0; ai < 2; ++ai) {
;             f32x4 bv[4][2][2];
; #pragma unroll
;             for (int m = 0; m < 4; ++m)
; #pragma unroll
;                 for (int bj = 0; bj < 2; ++bj) { const size_t off = (size_t)(row0 + ai * 128 + m * 16) * DM + col0 + bj * 128; bv[m][bj][0] = *(const f32x4*)(base + off); bv[m][bj][1] = *(const f32x4*)(base + off + 4); }
; #pragma unroll
;             for (int m = 0; m < 4; ++m) {
;                 const int row = row0 + ai * 128 + m * 16; float ss = 0.f;
; #pragma unroll
;                 for (int bj = 0; bj < 2; ++bj) {
;                     const size_t off = (size_t)row * DM + col0 + bj * 128;
;                     const f32x4 x0 = bv[m][bj][0] + acc[ai][bj][m][0] * alpha, x1 = bv[m][bj][1] + acc[ai][bj][m][1] * alpha;
;                     *(f32x4*)(out + off) = x0; *(f32x4*)(out + off + 4) = x1;
;                     u32x4 w; w.x = pk2(x0[0], x0[1]); w.y = pk2(x0[2], x0[3]); w.z = pk2(x1[0], x1[1]); w.w = pk2(x1[2], x1[3]);
;                     *(u32x4*)(xb + off) = w;
;                     ss += ((x0[0] * x0[0] + x0[1] * x0[1]) + (x0[2] * x0[2] + x0[3] * x0[3])) + ((x1[0] * x1[0] + x1[1] * x1[1]) + (x1[2] * x1[2] + x1[3] * x1[3]));
;                 }
;                 ss += __shfl_xor(ss, 16); ss += __shfl_xor(ss, 32);
;                 if (ssq && fq == 0) ssq[(size_t)row * 16 + u.pn * 4 + wc] = ss;
;             }
.LBB0_598:
	s_or_b64 exec, exec, s[40:41]
	s_waitcnt lgkmcnt(0)
	v_lshlrev_b64 v[84:85], 10, v[212:213]
	v_lshl_add_u64 v[88:89], v[84:85], 0, v[206:207]
	v_pk_fma_f32 v[82:83], v[192:193], v[82:83], v[154:155]
	v_pk_fma_f32 v[80:81], v[194:195], v[80:81], v[152:153]
	v_pk_fma_f32 v[76:77], v[194:195], v[76:77], v[144:145]
	v_lshl_add_u64 v[90:91], v[88:89], 2, s[24:25]
	v_pk_fma_f32 v[78:79], v[192:193], v[78:79], v[146:147]
	global_store_dwordx4 v[90:91], v[80:83], off sc1
	global_store_dwordx4 v[90:91], v[76:79], off offset:16 sc1
	v_cvt_pk_bf16_f32 v86, v76, v77
	v_pk_fma_f32 v[74:75], v[192:193], v[74:75], v[138:139]
	v_mul_f32_e32 v77, v77, v77
	v_fmac_f32_e32 v77, v76, v76
	v_mul_f32_e32 v76, v79, v79
	v_fmac_f32_e32 v76, v78, v78
	v_pk_fma_f32 v[72:73], v[194:195], v[72:73], v[136:137]
	v_cvt_pk_bf16_f32 v87, v78, v79
	v_add_f32_e32 v76, v77, v76
	v_mul_f32_e32 v77, v73, v73
	v_mul_f32_e32 v78, v75, v75
	v_cvt_pk_bf16_f32 v84, v80, v81
	v_mul_f32_e32 v81, v81, v81
	v_pk_fma_f32 v[70:71], v[192:193], v[70:71], v[134:135]
	v_pk_fma_f32 v[68:69], v[194:195], v[68:69], v[132:133]
	v_fmac_f32_e32 v77, v72, v72
	v_fmac_f32_e32 v78, v74, v74
	v_fmac_f32_e32 v81, v80, v80
	v_mul_f32_e32 v80, v83, v83
	v_add_f32_e32 v77, v77, v78
	v_mul_f32_e32 v78, v69, v69
	v_mul_f32_e32 v79, v71, v71
	v_fmac_f32_e32 v80, v82, v82
	v_fmac_f32_e32 v78, v68, v68
	v_fmac_f32_e32 v79, v70, v70
	v_add_f32_e32 v80, v81, v80
	v_add_f32_e32 v78, v78, v79
	v_add_f32_e32 v76, v80, v76
	v_add_f32_e32 v77, v77, v78
	v_add_f32_e32 v76, v76, v77
	ds_bpermute_b32 v77, v222, v76
	v_lshlrev_b64 v[88:89], 1, v[88:89]
	v_cvt_pk_bf16_f32 v85, v82, v83
	v_lshl_add_u64 v[92:93], s[2:3], 0, v[88:89]
	global_store_dwordx4 v[92:93], v[84:87], off
	global_store_dwordx4 v[90:91], v[72:75], off offset:512 sc1
	global_store_dwordx4 v[90:91], v[68:71], off offset:528 sc1
	v_or_b32_e32 v88, 0x100, v88
	v_cvt_pk_bf16_f32 v72, v72, v73
	v_cvt_pk_bf16_f32 v73, v74, v75
	v_cvt_pk_bf16_f32 v74, v68, v69
	s_waitcnt lgkmcnt(0)
	v_add_f32_e32 v68, v76, v77
	ds_bpermute_b32 v69, v221, v68
	v_cvt_pk_bf16_f32 v75, v70, v71
	v_lshl_add_u64 v[70:71], s[2:3], 0, v[88:89]
	global_store_dwordx4 v[70:71], v[72:75], off
	s_and_saveexec_b64 s[40:41], s[18:19]
	s_cbranch_execz .LBB0_600
	s_waitcnt lgkmcnt(0)
	v_add_f32_e32 v70, v68, v69
	v_lshlrev_b64 v[68:69], 6, v[212:213]
	v_lshl_add_u64 v[68:69], s[14:15], 0, v[68:69]
	v_lshl_add_u64 v[68:69], s[22:23], 2, v[68:69]
	s_lshl_b32 s8, s54, 2
	v_lshl_add_u64 v[68:69], v[68:69], 0, s[8:9]
	global_store_dword v[68:69], v70, off
.LBB0_600:
	s_or_b64 exec, exec, s[40:41]
	v_add_u32_e32 v130, 0x80, v208
	v_ashrrev_i32_e32 v131, 31, v130
	s_waitcnt lgkmcnt(0)
	v_lshlrev_b64 v[68:69], 12, v[130:131]
	v_lshl_add_u64 v[68:69], v[210:211], 0, v[68:69]
	global_load_dwordx4 v[132:135], v[68:69], off offset:16
	global_load_dwordx4 v[136:139], v[68:69], off
	global_load_dwordx4 v[116:119], v[68:69], off offset:528
	global_load_dwordx4 v[120:123], v[68:69], off offset:512
	v_add_u32_e32 v128, 0x90, v208
	v_ashrrev_i32_e32 v129, 31, v128
	v_lshlrev_b64 v[68:69], 12, v[128:129]
	v_add_u32_e32 v126, 0xa0, v208
	v_lshl_add_u64 v[68:69], v[210:211], 0, v[68:69]
	v_ashrrev_i32_e32 v127, 31, v126
	global_load_dwordx4 v[108:111], v[68:69], off offset:16
	global_load_dwordx4 v[112:115], v[68:69], off
	global_load_dwordx4 v[100:103], v[68:69], off offset:528
	global_load_dwordx4 v[104:107], v[68:69], off offset:512
	v_lshlrev_b64 v[68:69], 12, v[126:127]
	v_add_u32_e32 v124, 0xb0, v208
	v_lshl_add_u64 v[68:69], v[210:211], 0, v[68:69]
	v_ashrrev_i32_e32 v125, 31, v124
	global_load_dwordx4 v[92:95], v[68:69], off offset:16
	global_load_dwordx4 v[96:99], v[68:69], off
	global_load_dwordx4 v[76:79], v[68:69], off offset:528
	global_load_dwordx4 v[84:87], v[68:69], off offset:512
	v_lshlrev_b64 v[68:69], 12, v[124:125]
	v_lshl_add_u64 v[72:73], v[210:211], 0, v[68:69]
	global_load_dwordx4 v[80:83], v[72:73], off offset:16
	global_load_dwordx4 v[88:91], v[72:73], off
	global_load_dwordx4 v[68:71], v[72:73], off offset:528
	s_nop 0
	global_load_dwordx4 v[72:75], v[72:73], off offset:512
	v_lshlrev_b64 v[140:141], 10, v[130:131]
	v_lshl_add_u64 v[140:141], v[140:141], 0, v[206:207]
	v_mov_b32_e32 v193, v192
	s_waitcnt vmcnt(15)
	v_pk_fma_f32 v[60:61], v[194:195], v[60:61], v[132:133]
	s_waitcnt vmcnt(14)
	v_pk_fma_f32 v[66:67], v[192:193], v[66:67], v[138:139]
	v_pk_fma_f32 v[64:65], v[194:195], v[64:65], v[136:137]
	v_lshl_add_u64 v[136:137], v[140:141], 2, s[24:25]
	v_pk_fma_f32 v[62:63], v[192:193], v[62:63], v[134:135]
	global_store_dwordx4 v[136:137], v[64:67], off sc1
	global_store_dwordx4 v[136:137], v[60:63], off offset:16 sc1
	v_cvt_pk_bf16_f32 v132, v64, v65
	v_cvt_pk_bf16_f32 v134, v60, v61
	v_mul_f32_e32 v65, v65, v65
	v_mul_f32_e32 v61, v61, v61
	v_fmac_f32_e32 v65, v64, v64
	v_mul_f32_e32 v64, v67, v67
	v_fmac_f32_e32 v61, v60, v60
	v_mul_f32_e32 v60, v63, v63
	v_lshlrev_b64 v[138:139], 1, v[140:141]
	v_fmac_f32_e32 v64, v66, v66
	v_fmac_f32_e32 v60, v62, v62
	v_cvt_pk_bf16_f32 v133, v66, v67
	v_cvt_pk_bf16_f32 v135, v62, v63
	v_lshl_add_u64 v[140:141], s[2:3], 0, v[138:139]
	v_add_f32_e32 v64, v65, v64
	v_add_f32_e32 v60, v61, v60
	s_waitcnt vmcnt(14)
	v_pk_fma_f32 v[58:59], v[192:193], v[58:59], v[122:123]
	v_pk_fma_f32 v[56:57], v[194:195], v[56:57], v[120:121]
	v_pk_fma_f32 v[52:53], v[194:195], v[52:53], v[116:117]
	global_store_dwordx4 v[140:141], v[132:135], off
	v_add_f32_e32 v66, v64, v60
	v_pk_fma_f32 v[54:55], v[192:193], v[54:55], v[118:119]
	global_store_dwordx4 v[136:137], v[56:59], off offset:512 sc1
	global_store_dwordx4 v[136:137], v[52:55], off offset:528 sc1
	v_cvt_pk_bf16_f32 v60, v56, v57
	v_cvt_pk_bf16_f32 v62, v52, v53
	v_mul_f32_e32 v57, v57, v57
	v_mul_f32_e32 v53, v53, v53
	v_fmac_f32_e32 v57, v56, v56
	v_mul_f32_e32 v56, v59, v59
	v_fmac_f32_e32 v53, v52, v52
	v_mul_f32_e32 v52, v55, v55
	v_fmac_f32_e32 v56, v58, v58
	v_fmac_f32_e32 v52, v54, v54
	v_add_f32_e32 v56, v57, v56
	v_add_f32_e32 v52, v53, v52
	v_add_f32_e32 v52, v56, v52
	v_add_f32_e32 v52, v66, v52
	ds_bpermute_b32 v53, v222, v52
	v_or_b32_e32 v138, 0x100, v138
	v_cvt_pk_bf16_f32 v61, v58, v59
	v_cvt_pk_bf16_f32 v63, v54, v55
	v_lshl_add_u64 v[64:65], s[2:3], 0, v[138:139]
	s_waitcnt lgkmcnt(0)
	v_add_f32_e32 v52, v52, v53
	ds_bpermute_b32 v53, v221, v52
	global_store_dwordx4 v[64:65], v[60:63], off
	s_and_saveexec_b64 s[40:41], s[18:19]
	s_cbranch_execz .LBB0_602
	s_waitcnt lgkmcnt(0)
	v_add_f32_e32 v54, v52, v53
	v_lshlrev_b64 v[52:53], 6, v[130:131]
	v_lshl_add_u64 v[52:53], s[14:15], 0, v[52:53]
	v_lshl_add_u64 v[52:53], s[22:23], 2, v[52:53]
	s_lshl_b32 s8, s54, 2
	v_lshl_add_u64 v[52:53], v[52:53], 0, s[8:9]
	global_store_dword v[52:53], v54, off
; __device__ __forceinline__ unsigned pk2(float lo, float hi) { return pg8::cvt_pk_bf16(lo, hi); }
;     __device__ __forceinline__ void operator()(const pg8::f32x4 (&acc)[2][2][4][2], const pg8::Unit& u, int wr, int wc, int fr, int fq) const {
;     ...
;             for (int m = 0; m < 4; ++m) {
;                 const int row = row0 + ai * 128 + m * 16; float ss = 0.f;
; #pragma unroll
;                 for (int bj = 0; bj < 2; ++bj) {
;                     const size_t off = (size_t)row * DM + col0 + bj * 128;
;                     const f32x4 x0 = bv[m][bj][0] + acc[ai][bj][m][0] * alpha, x1 = bv[m][bj][1] + acc[ai][bj][m][1] * alpha;
;                     *(f32x4*)(out + off) = x0; *(f32x4*)(out + off + 4) = x1;
;                     u32x4 w; w.x = pk2(x0[0], x0[1]); w.y = pk2(x0[2], x0[3]); w.z = pk2(x1[0], x1[1]); w.w = pk2(x1[2], x1[3]);
;                     *(u32x4*)(xb + off) = w;
;                     ss += ((x0[0] * x0[0] + x0[1] * x0[1]) + (x0[2] * x0[2] + x0[3] * x0[3])) + ((x1[0] * x1[0] + x1[1] * x1[1]) + (x1[2] * x1[2] + x1[3] * x1[3]));
;                 }
;                 ss += __shfl_xor(ss, 16); ss += __shfl_xor(ss, 32);
;                 if (ssq && fq == 0) ssq[(size_t)row * 16 + u.pn * 4 + wc] = ss;
;             }
.LBB0_602:
	s_or_b64 exec, exec, s[40:41]
	s_waitcnt lgkmcnt(0)
	v_lshlrev_b64 v[52:53], 10, v[128:129]
	v_lshl_add_u64 v[56:57], v[52:53], 0, v[206:207]
	s_waitcnt vmcnt(16)
	v_pk_fma_f32 v[50:51], v[192:193], v[50:51], v[114:115]
	v_pk_fma_f32 v[48:49], v[194:195], v[48:49], v[112:113]
	v_pk_fma_f32 v[44:45], v[194:195], v[44:45], v[108:109]
	v_lshl_add_u64 v[58:59], v[56:57], 2, s[24:25]
	v_pk_fma_f32 v[46:47], v[192:193], v[46:47], v[110:111]
	global_store_dwordx4 v[58:59], v[48:51], off sc1
	global_store_dwordx4 v[58:59], v[44:47], off offset:16 sc1
	v_cvt_pk_bf16_f32 v54, v44, v45
	s_waitcnt vmcnt(16)
	v_pk_fma_f32 v[42:43], v[192:193], v[42:43], v[106:107]
	v_mul_f32_e32 v45, v45, v45
	v_fmac_f32_e32 v45, v44, v44
	v_mul_f32_e32 v44, v47, v47
	v_fmac_f32_e32 v44, v46, v46
	v_pk_fma_f32 v[40:41], v[194:195], v[40:41], v[104:105]
	v_cvt_pk_bf16_f32 v55, v46, v47
	v_add_f32_e32 v44, v45, v44
	v_mul_f32_e32 v45, v41, v41
	v_mul_f32_e32 v46, v43, v43
	v_cvt_pk_bf16_f32 v52, v48, v49
	v_mul_f32_e32 v49, v49, v49
	v_pk_fma_f32 v[38:39], v[192:193], v[38:39], v[102:103]
	v_pk_fma_f32 v[36:37], v[194:195], v[36:37], v[100:101]
	v_fmac_f32_e32 v45, v40, v40
	v_fmac_f32_e32 v46, v42, v42
	v_fmac_f32_e32 v49, v48, v48
	v_mul_f32_e32 v48, v51, v51
	v_add_f32_e32 v45, v45, v46
	v_mul_f32_e32 v46, v37, v37
	v_mul_f32_e32 v47, v39, v39
	v_fmac_f32_e32 v48, v50, v50
	v_fmac_f32_e32 v46, v36, v36
	v_fmac_f32_e32 v47, v38, v38
	v_add_f32_e32 v48, v49, v48
	v_add_f32_e32 v46, v46, v47
	v_add_f32_e32 v44, v48, v44
	v_add_f32_e32 v45, v45, v46
	v_add_f32_e32 v44, v44, v45
	ds_bpermute_b32 v45, v222, v44
	v_lshlrev_b64 v[56:57], 1, v[56:57]
	v_cvt_pk_bf16_f32 v53, v50, v51
	v_lshl_add_u64 v[60:61], s[2:3], 0, v[56:57]
	global_store_dwordx4 v[60:61], v[52:55], off
	global_store_dwordx4 v[58:59], v[40:43], off offset:512 sc1
	global_store_dwordx4 v[58:59], v[36:39], off offset:528 sc1
	v_or_b32_e32 v56, 0x100, v56
	v_cvt_pk_bf16_f32 v40, v40, v41
	v_cvt_pk_bf16_f32 v41, v42, v43
	v_cvt_pk_bf16_f32 v42, v36, v37
	s_waitcnt lgkmcnt(0)
	v_add_f32_e32 v36, v44, v45
	ds_bpermute_b32 v37, v221, v36
	v_cvt_pk_bf16_f32 v43, v38, v39
	v_lshl_add_u64 v[38:39], s[2:3], 0, v[56:57]
	global_store_dwordx4 v[38:39], v[40:43], off
	s_and_saveexec_b64 s[40:41], s[18:19]
	s_cbranch_execz .LBB0_604
	s_waitcnt lgkmcnt(0)
	v_add_f32_e32 v38, v36, v37
	v_lshlrev_b64 v[36:37], 6, v[128:129]
	v_lshl_add_u64 v[36:37], s[14:15], 0, v[36:37]
	v_lshl_add_u64 v[36:37], s[22:23], 2, v[36:37]
	s_lshl_b32 s8, s54, 2
	v_lshl_add_u64 v[36:37], v[36:37], 0, s[8:9]
	global_store_dword v[36:37], v38, off
; __device__ __forceinline__ unsigned pk2(float lo, float hi) { return pg8::cvt_pk_bf16(lo, hi); }
;     __device__ __forceinline__ void operator()(const pg8::f32x4 (&acc)[2][2][4][2], const pg8::Unit& u, int wr, int wc, int fr, int fq) const {
;     ...
;             for (int m = 0; m < 4; ++m) {
;                 const int row = row0 + ai * 128 + m * 16; float ss = 0.f;
; #pragma unroll
;                 for (int bj = 0; bj < 2; ++bj) {
;                     const size_t off = (size_t)row * DM + col0 + bj * 128;
;                     const f32x4 x0 = bv[m][bj][0] + acc[ai][bj][m][0] * alpha, x1 = bv[m][bj][1] + acc[ai][bj][m][1] * alpha;
;                     *(f32x4*)(out + off) = x0; *(f32x4*)(out + off + 4) = x1;
;                     u32x4 w; w.x = pk2(x0[0], x0[1]); w.y = pk2(x0[2], x0[3]); w.z = pk2(x1[0], x1[1]); w.w = pk2(x1[2], x1[3]);
;                     *(u32x4*)(xb + off) = w;
;                     ss += ((x0[0] * x0[0] + x0[1] * x0[1]) + (x0[2] * x0[2] + x0[3] * x0[3])) + ((x1[0] * x1[0] + x1[1] * x1[1]) + (x1[2] * x1[2] + x1[3] * x1[3]));
;                 }
;                 ss += __shfl_xor(ss, 16); ss += __shfl_xor(ss, 32);
;                 if (ssq && fq == 0) ssq[(size_t)row * 16 + u.pn * 4 + wc] = ss;
;             }
;             asm volatile("" ::: "memory");
;         }
.LBB0_604:
	s_or_b64 exec, exec, s[40:41]
	s_waitcnt lgkmcnt(0)
	v_lshlrev_b64 v[36:37], 10, v[126:127]
	v_lshl_add_u64 v[40:41], v[36:37], 0, v[206:207]
	v_mov_b32_e32 v193, v192
	s_waitcnt vmcnt(18)
	v_pk_fma_f32 v[30:31], v[192:193], v[30:31], v[98:99]
	v_pk_fma_f32 v[28:29], v[194:195], v[28:29], v[96:97]
	v_pk_fma_f32 v[24:25], v[194:195], v[24:25], v[92:93]
	v_lshl_add_u64 v[42:43], v[40:41], 2, s[24:25]
	v_pk_fma_f32 v[26:27], v[192:193], v[26:27], v[94:95]
	global_store_dwordx4 v[42:43], v[28:31], off sc1
	global_store_dwordx4 v[42:43], v[24:27], off offset:16 sc1
	v_cvt_pk_bf16_f32 v38, v24, v25
	s_waitcnt vmcnt(18)
	v_pk_fma_f32 v[22:23], v[192:193], v[22:23], v[86:87]
	v_mul_f32_e32 v25, v25, v25
	v_fmac_f32_e32 v25, v24, v24
	v_mul_f32_e32 v24, v27, v27
	v_fmac_f32_e32 v24, v26, v26
	v_pk_fma_f32 v[20:21], v[194:195], v[20:21], v[84:85]
	v_cvt_pk_bf16_f32 v39, v26, v27
	v_add_f32_e32 v24, v25, v24
	v_mul_f32_e32 v25, v21, v21
	v_mul_f32_e32 v26, v23, v23
	v_cvt_pk_bf16_f32 v36, v28, v29
	v_mul_f32_e32 v29, v29, v29
	v_pk_fma_f32 v[18:19], v[192:193], v[18:19], v[78:79]
	v_pk_fma_f32 v[16:17], v[194:195], v[16:17], v[76:77]
	v_fmac_f32_e32 v25, v20, v20
	v_fmac_f32_e32 v26, v22, v22
	v_fmac_f32_e32 v29, v28, v28
	v_mul_f32_e32 v28, v31, v31
	v_add_f32_e32 v25, v25, v26
	v_mul_f32_e32 v26, v17, v17
	v_mul_f32_e32 v27, v19, v19
	v_fmac_f32_e32 v28, v30, v30
	v_fmac_f32_e32 v26, v16, v16
	v_fmac_f32_e32 v27, v18, v18
	v_add_f32_e32 v28, v29, v28
	v_add_f32_e32 v26, v26, v27
	v_add_f32_e32 v24, v28, v24
	v_add_f32_e32 v25, v25, v26
	v_add_f32_e32 v24, v24, v25
	ds_bpermute_b32 v25, v222, v24
	v_lshlrev_b64 v[40:41], 1, v[40:41]
	v_cvt_pk_bf16_f32 v37, v30, v31
	v_lshl_add_u64 v[44:45], s[2:3], 0, v[40:41]
	global_store_dwordx4 v[44:45], v[36:39], off
	global_store_dwordx4 v[42:43], v[20:23], off offset:512 sc1
	global_store_dwordx4 v[42:43], v[16:19], off offset:528 sc1
	v_or_b32_e32 v40, 0x100, v40
	v_cvt_pk_bf16_f32 v20, v20, v21
	v_cvt_pk_bf16_f32 v21, v22, v23
	v_cvt_pk_bf16_f32 v22, v16, v17
	s_waitcnt lgkmcnt(0)
	v_add_f32_e32 v16, v24, v25
	ds_bpermute_b32 v17, v221, v16
	v_cvt_pk_bf16_f32 v23, v18, v19
	v_lshl_add_u64 v[18:19], s[2:3], 0, v[40:41]
	global_store_dwordx4 v[18:19], v[20:23], off
	s_and_saveexec_b64 s[40:41], s[18:19]
	s_cbranch_execz .LBB0_606
	s_waitcnt lgkmcnt(0)
	v_add_f32_e32 v18, v16, v17
	v_lshlrev_b64 v[16:17], 6, v[126:127]
	v_lshl_add_u64 v[16:17], s[14:15], 0, v[16:17]
	v_lshl_add_u64 v[16:17], s[22:23], 2, v[16:17]
	s_lshl_b32 s8, s54, 2
	v_lshl_add_u64 v[16:17], v[16:17], 0, s[8:9]
	global_store_dword v[16:17], v18, off
.LBB0_606:
	s_or_b64 exec, exec, s[40:41]
	s_waitcnt lgkmcnt(0)
	v_lshlrev_b64 v[16:17], 10, v[124:125]
	v_lshl_add_u64 v[20:21], v[16:17], 0, v[206:207]
	s_waitcnt vmcnt(20)
	v_pk_fma_f32 v[14:15], v[192:193], v[14:15], v[90:91]
	v_pk_fma_f32 v[12:13], v[194:195], v[12:13], v[88:89]
	v_pk_fma_f32 v[8:9], v[194:195], v[8:9], v[80:81]
	v_lshl_add_u64 v[22:23], v[20:21], 2, s[24:25]
	v_pk_fma_f32 v[10:11], v[192:193], v[10:11], v[82:83]
	global_store_dwordx4 v[22:23], v[12:15], off sc1
	global_store_dwordx4 v[22:23], v[8:11], off offset:16 sc1
	v_cvt_pk_bf16_f32 v18, v8, v9
	s_waitcnt vmcnt(20)
	v_pk_fma_f32 v[6:7], v[192:193], v[6:7], v[74:75]
	v_mul_f32_e32 v9, v9, v9
	v_fmac_f32_e32 v9, v8, v8
	v_mul_f32_e32 v8, v11, v11
	v_fmac_f32_e32 v8, v10, v10
	v_pk_fma_f32 v[4:5], v[194:195], v[4:5], v[72:73]
	v_cvt_pk_bf16_f32 v19, v10, v11
	v_add_f32_e32 v8, v9, v8
	v_mul_f32_e32 v9, v5, v5
	v_mul_f32_e32 v10, v7, v7
	v_cvt_pk_bf16_f32 v16, v12, v13
	v_mul_f32_e32 v13, v13, v13
	v_pk_fma_f32 v[2:3], v[192:193], v[2:3], v[70:71]
	v_pk_fma_f32 v[0:1], v[194:195], v[0:1], v[68:69]
	v_fmac_f32_e32 v9, v4, v4
	v_fmac_f32_e32 v10, v6, v6
	v_fmac_f32_e32 v13, v12, v12
	v_mul_f32_e32 v12, v15, v15
	v_add_f32_e32 v9, v9, v10
	v_mul_f32_e32 v10, v1, v1
	v_mul_f32_e32 v11, v3, v3
	v_fmac_f32_e32 v12, v14, v14
	v_fmac_f32_e32 v10, v0, v0
	v_fmac_f32_e32 v11, v2, v2
	v_add_f32_e32 v12, v13, v12
	v_add_f32_e32 v10, v10, v11
	v_add_f32_e32 v8, v12, v8
	v_add_f32_e32 v9, v9, v10
	v_add_f32_e32 v8, v8, v9
	ds_bpermute_b32 v9, v222, v8
	v_lshlrev_b64 v[20:21], 1, v[20:21]
	v_cvt_pk_bf16_f32 v17, v14, v15
	v_lshl_add_u64 v[24:25], s[2:3], 0, v[20:21]
	global_store_dwordx4 v[24:25], v[16:19], off
	global_store_dwordx4 v[22:23], v[4:7], off offset:512 sc1
	global_store_dwordx4 v[22:23], v[0:3], off offset:528 sc1
	v_or_b32_e32 v20, 0x100, v20
	v_cvt_pk_bf16_f32 v4, v4, v5
	v_cvt_pk_bf16_f32 v5, v6, v7
	v_cvt_pk_bf16_f32 v6, v0, v1
	s_waitcnt lgkmcnt(0)
	v_add_f32_e32 v0, v8, v9
	ds_bpermute_b32 v1, v221, v0
	v_cvt_pk_bf16_f32 v7, v2, v3
	v_lshl_add_u64 v[2:3], s[2:3], 0, v[20:21]
	global_store_dwordx4 v[2:3], v[4:7], off
	s_and_saveexec_b64 s[40:41], s[18:19]
	s_cbranch_execz .LBB0_608
	s_waitcnt lgkmcnt(0)
	v_add_f32_e32 v2, v0, v1
	v_lshlrev_b64 v[0:1], 6, v[124:125]
	v_lshl_add_u64 v[0:1], s[14:15], 0, v[0:1]
	v_lshl_add_u64 v[0:1], s[22:23], 2, v[0:1]
	s_lshl_b32 s8, s54, 2
	v_lshl_add_u64 v[0:1], v[0:1], 0, s[8:9]
	global_store_dword v[0:1], v2, off
